# E27: SGU phase loop de-serialised: all 8 loads of a chunk issued together and waited once (3 late U loads become register copies); on E23
# speedup vs baseline: 1.0024x; 1.0003x over previous
.LBB0_1319:
	v_lshl_add_u64 v[66:67], s[48:49], 0, v[102:103]
	v_add_co_u32_e32 v78, vcc, 0x4c300000, v66
	v_lshl_add_u64 v[104:105], s[48:49], 0, v[100:101]
	s_nop 0
	v_addc_co_u32_e32 v79, vcc, 0, v67, vcc
	v_lshl_add_u64 v[106:107], s[48:49], 0, v[96:97]
	s_mov_b32 s8, 0x51308000
	v_add_co_u32_e32 v192, vcc, s8, v106
	s_nop 1
	v_addc_co_u32_e32 v193, vcc, 0, v107, vcc
	s_mov_b32 s8, 0x51310000
	v_add_co_u32_e32 v194, vcc, s8, v106
	s_nop 1
	v_addc_co_u32_e32 v195, vcc, 0, v107, vcc
	s_mov_b32 s8, 0x51318000
	v_add_co_u32_e32 v196, vcc, s8, v106
	s_nop 1
	v_addc_co_u32_e32 v197, vcc, 0, v107, vcc
	global_load_dwordx4 v[66:69], v[78:79], off
	global_load_dwordx4 v[70:73], v[78:79], off offset:64
	global_load_dwordx4 v[74:77], v[78:79], off offset:128
	s_nop 0
	global_load_dwordx4 v[78:81], v[78:79], off offset:192
	global_load_dwordx2 v[104:105], v[104:105], off
	global_load_dwordx2 v[186:187], v[192:193], off
	global_load_dwordx2 v[188:189], v[194:195], off
	global_load_dwordx2 v[190:191], v[196:197], off
	s_add_i32 s2, s2, s12
	v_lshl_add_u64 v[100:101], v[100:101], 0, s[18:19]
	v_lshl_add_u64 v[102:103], v[102:103], 0, s[22:23]
	s_cmpk_gt_i32 s2, 0x13f
	s_waitcnt vmcnt(7)
	v_mfma_f32_16x16x32_bf16 v[82:85], v[66:69], v[10:13], 0
	s_waitcnt vmcnt(0)
	v_lshlrev_b32_e32 v107, 16, v105
	v_mfma_f32_16x16x32_bf16 v[82:85], v[70:73], v[2:5], v[82:85]
	v_lshlrev_b32_e32 v106, 16, v104
	v_and_b32_e32 v105, 0xffff0000, v105
	v_and_b32_e32 v104, 0xffff0000, v104
	v_mfma_f32_16x16x32_bf16 v[82:85], v[74:77], v[6:9], v[82:85]
	v_mfma_f32_16x16x32_bf16 v[82:85], v[78:81], v[34:37], v[82:85]
	s_nop 7
	v_mov_b32_e32 v109, v84
	v_mov_b32_e32 v84, v83
	v_mov_b32_e32 v108, v82
	v_pk_add_f32 v[82:83], v[92:93], v[84:85]
	v_pk_add_f32 v[108:109], v[92:93], v[108:109]
	v_pk_mul_f32 v[82:83], v[82:83], v[104:105]
	v_pk_mul_f32 v[106:107], v[108:109], v[106:107]
	v_and_b32_sdwa v104, v83, v1 dst_sel:DWORD dst_unused:UNUSED_PAD src0_sel:WORD_1 src1_sel:DWORD
	v_and_b32_sdwa v105, v82, v1 dst_sel:DWORD dst_unused:UNUSED_PAD src0_sel:WORD_1 src1_sel:DWORD
	v_and_b32_sdwa v84, v107, v1 dst_sel:DWORD dst_unused:UNUSED_PAD src0_sel:WORD_1 src1_sel:DWORD
	v_and_b32_sdwa v85, v106, v1 dst_sel:DWORD dst_unused:UNUSED_PAD src0_sel:WORD_1 src1_sel:DWORD
	v_add3_u32 v83, v83, v104, s76
	v_add3_u32 v82, v82, v105, s76
	v_add3_u32 v85, v106, v85, s76
	v_add3_u32 v84, v107, v84, s76
	v_and_b32_e32 v83, 0xffff0000, v83
	v_and_b32_e32 v82, 0xffff0000, v82
	v_or_b32_sdwa v83, v83, v84 dst_sel:DWORD dst_unused:UNUSED_PAD src0_sel:DWORD src1_sel:WORD_1
	v_or_b32_sdwa v82, v82, v85 dst_sel:DWORD dst_unused:UNUSED_PAD src0_sel:DWORD src1_sel:WORD_1
	v_lshl_add_u64 v[84:85], s[48:49], 0, v[98:99]
	global_store_dwordx2 v[84:85], v[82:83], off
	s_nop 0
	v_mov_b32_e32 v104, v186
	v_mov_b32_e32 v105, v187
	v_mfma_f32_16x16x32_bf16 v[82:85], v[66:69], v[14:17], 0
	v_lshl_add_u64 v[96:97], v[96:97], 0, s[18:19]
	v_lshl_add_u64 v[98:99], v[98:99], 0, s[14:15]
	v_mfma_f32_16x16x32_bf16 v[82:85], v[70:73], v[18:21], v[82:85]
	v_lshlrev_b32_e32 v109, 16, v105
	v_mfma_f32_16x16x32_bf16 v[82:85], v[74:77], v[22:25], v[82:85]
	v_lshlrev_b32_e32 v108, 16, v104
	v_and_b32_e32 v105, 0xffff0000, v105
	v_and_b32_e32 v104, 0xffff0000, v104
	v_mfma_f32_16x16x32_bf16 v[82:85], v[78:81], v[26:29], v[82:85]
	s_nop 7
	v_mov_b32_e32 v111, v84
	v_mov_b32_e32 v84, v83
	v_mov_b32_e32 v110, v82
	v_pk_add_f32 v[82:83], v[90:91], v[84:85]
	v_pk_add_f32 v[110:111], v[90:91], v[110:111]
	v_pk_mul_f32 v[82:83], v[82:83], v[104:105]
	v_pk_mul_f32 v[108:109], v[110:111], v[108:109]
	v_and_b32_sdwa v104, v83, v1 dst_sel:DWORD dst_unused:UNUSED_PAD src0_sel:WORD_1 src1_sel:DWORD
	v_and_b32_sdwa v84, v109, v1 dst_sel:DWORD dst_unused:UNUSED_PAD src0_sel:WORD_1 src1_sel:DWORD
	v_and_b32_sdwa v105, v82, v1 dst_sel:DWORD dst_unused:UNUSED_PAD src0_sel:WORD_1 src1_sel:DWORD
	v_add3_u32 v83, v83, v104, s76
	v_and_b32_sdwa v85, v108, v1 dst_sel:DWORD dst_unused:UNUSED_PAD src0_sel:WORD_1 src1_sel:DWORD
	v_add3_u32 v84, v109, v84, s76
	v_add3_u32 v82, v82, v105, s76
	v_and_b32_e32 v83, 0xffff0000, v83
	v_lshl_add_u64 v[104:105], s[48:49], 0, v[94:95]
	v_add3_u32 v85, v108, v85, s76
	v_and_b32_e32 v82, 0xffff0000, v82
	v_or_b32_sdwa v83, v83, v84 dst_sel:DWORD dst_unused:UNUSED_PAD src0_sel:DWORD src1_sel:WORD_1
	v_add_co_u32_e32 v84, vcc, s9, v104
	v_or_b32_sdwa v82, v82, v85 dst_sel:DWORD dst_unused:UNUSED_PAD src0_sel:DWORD src1_sel:WORD_1
	s_nop 0
	v_addc_co_u32_e32 v85, vcc, 0, v105, vcc
	global_store_dwordx2 v[84:85], v[82:83], off offset:2048
	s_nop 0
	v_mov_b32_e32 v108, v188
	v_mov_b32_e32 v109, v189
	v_mfma_f32_16x16x32_bf16 v[82:85], v[66:69], v[30:33], 0
	v_lshl_add_u64 v[94:95], v[94:95], 0, s[14:15]
	v_lshlrev_b32_e32 v111, 16, v109
	v_mfma_f32_16x16x32_bf16 v[82:85], v[70:73], v[38:41], v[82:85]
	v_lshlrev_b32_e32 v110, 16, v108
	v_and_b32_e32 v109, 0xffff0000, v109
	v_and_b32_e32 v108, 0xffff0000, v108
	v_mfma_f32_16x16x32_bf16 v[82:85], v[74:77], v[42:45], v[82:85]
	v_mfma_f32_16x16x32_bf16 v[82:85], v[78:81], v[46:49], v[82:85]
	v_mfma_f32_16x16x32_bf16 v[66:69], v[66:69], v[50:53], 0
	v_mfma_f32_16x16x32_bf16 v[66:69], v[70:73], v[54:57], v[66:69]
	s_nop 5
	v_mov_b32_e32 v113, v84
	v_mov_b32_e32 v84, v83
	v_mov_b32_e32 v112, v82
	v_pk_add_f32 v[82:83], v[88:89], v[84:85]
	v_pk_add_f32 v[112:113], v[88:89], v[112:113]
	v_pk_mul_f32 v[82:83], v[82:83], v[108:109]
	v_pk_mul_f32 v[110:111], v[112:113], v[110:111]
	v_and_b32_sdwa v108, v83, v1 dst_sel:DWORD dst_unused:UNUSED_PAD src0_sel:WORD_1 src1_sel:DWORD
	v_and_b32_sdwa v84, v111, v1 dst_sel:DWORD dst_unused:UNUSED_PAD src0_sel:WORD_1 src1_sel:DWORD
	v_and_b32_sdwa v109, v82, v1 dst_sel:DWORD dst_unused:UNUSED_PAD src0_sel:WORD_1 src1_sel:DWORD
	v_add3_u32 v83, v83, v108, s76
	v_and_b32_sdwa v85, v110, v1 dst_sel:DWORD dst_unused:UNUSED_PAD src0_sel:WORD_1 src1_sel:DWORD
	v_add3_u32 v84, v111, v84, s76
	v_add3_u32 v82, v82, v109, s76
	v_and_b32_e32 v83, 0xffff0000, v83
	v_add3_u32 v85, v110, v85, s76
	v_and_b32_e32 v82, 0xffff0000, v82
	v_or_b32_sdwa v83, v83, v84 dst_sel:DWORD dst_unused:UNUSED_PAD src0_sel:DWORD src1_sel:WORD_1
	v_add_co_u32_e32 v84, vcc, s63, v104
	v_or_b32_sdwa v82, v82, v85 dst_sel:DWORD dst_unused:UNUSED_PAD src0_sel:DWORD src1_sel:WORD_1
	s_nop 0
	v_addc_co_u32_e32 v85, vcc, 0, v105, vcc
	global_store_dwordx2 v[84:85], v[82:83], off offset:2048
	s_nop 0
	v_mov_b32_e32 v70, v190
	v_mov_b32_e32 v71, v191
	v_mfma_f32_16x16x32_bf16 v[66:69], v[74:77], v[58:61], v[66:69]
	v_lshlrev_b32_e32 v73, 16, v71
	v_mfma_f32_16x16x32_bf16 v[66:69], v[78:81], v[62:65], v[66:69]
	v_lshlrev_b32_e32 v72, 16, v70
	v_and_b32_e32 v71, 0xffff0000, v71
	v_and_b32_e32 v70, 0xffff0000, v70
	s_nop 4
	v_mov_b32_e32 v75, v68
	v_mov_b32_e32 v68, v67
	v_mov_b32_e32 v74, v66
	v_pk_add_f32 v[66:67], v[86:87], v[68:69]
	v_pk_add_f32 v[74:75], v[86:87], v[74:75]
	v_pk_mul_f32 v[66:67], v[66:67], v[70:71]
	v_pk_mul_f32 v[72:73], v[74:75], v[72:73]
	v_and_b32_sdwa v70, v67, v1 dst_sel:DWORD dst_unused:UNUSED_PAD src0_sel:WORD_1 src1_sel:DWORD
	v_and_b32_sdwa v68, v73, v1 dst_sel:DWORD dst_unused:UNUSED_PAD src0_sel:WORD_1 src1_sel:DWORD
	v_and_b32_sdwa v71, v66, v1 dst_sel:DWORD dst_unused:UNUSED_PAD src0_sel:WORD_1 src1_sel:DWORD
	v_add3_u32 v67, v67, v70, s76
	v_and_b32_sdwa v69, v72, v1 dst_sel:DWORD dst_unused:UNUSED_PAD src0_sel:WORD_1 src1_sel:DWORD
	v_add3_u32 v68, v73, v68, s76
	v_add3_u32 v66, v66, v71, s76
	v_and_b32_e32 v67, 0xffff0000, v67
	v_add3_u32 v69, v72, v69, s76
	v_and_b32_e32 v66, 0xffff0000, v66
	v_or_b32_sdwa v67, v67, v68 dst_sel:DWORD dst_unused:UNUSED_PAD src0_sel:DWORD src1_sel:WORD_1
	v_add_co_u32_e32 v68, vcc, 0x30000, v104
	v_or_b32_sdwa v66, v66, v69 dst_sel:DWORD dst_unused:UNUSED_PAD src0_sel:DWORD src1_sel:WORD_1
	s_nop 0
	v_addc_co_u32_e32 v69, vcc, 0, v105, vcc
	global_store_dwordx2 v[68:69], v[66:67], off offset:2048
	s_cbranch_scc0 .LBB0_1319
